# hgrn_a: cumsum bpermute hops of the 8 channels issued together per round (counted lgkmcnt); layer-1 lower-bound logit loads hoisted into one batch
# baseline (speedup 1.0000x reference)
.LBB0_311:
	s_lshl_b32 s2, s2, 2
	v_mov_b32_e32 v16, s2
	s_waitcnt lgkmcnt(0)
	v_mov_b32_e32 v17, v92
	s_nop 0
	v_mov_b32_e32 v16, v93
	v_sub_f32_e32 v16, v17, v16
	v_mul_f32_e32 v16, 0x3fb8aa3b, v16
	v_exp_f32_e32 v16, v16
	s_nop 0
	v_add_f32_e32 v16, 1.0, v16
	v_rcp_f32_e32 v60, v16
.LBB0_312:
	s_waitcnt vmcnt(0)
	v_lshlrev_b32_e32 v17, 16, v15
	v_max_f32_e32 v17, v17, v17
	s_mov_b32 s8, 0xc1f00000
	v_med3_f32 v17, v17, s8, v184
	v_mul_f32_e32 v17, 0xbfb8aa3b, v17
	v_exp_f32_e32 v17, v17
	v_sub_f32_e32 v16, 1.0, v19
	s_mov_b32 s9, 0x3f317217
	s_mov_b32 s26, 0x7f800000
	v_add_f32_e32 v18, 1.0, v17
	v_rcp_f32_e32 v18, v18
	s_nop 0
	v_fmac_f32_e32 v19, v18, v16
	v_cmp_gt_f32_e32 vcc, s75, v19
	s_nop 1
	v_cndmask_b32_e64 v20, 0, 32, vcc
	v_ldexp_f32 v19, v19, v20
	v_log_f32_e32 v19, v19
	s_nop 0
	v_mul_f32_e32 v20, 0x3f317217, v19
	v_fma_f32 v20, v19, s9, -v20
	v_fmac_f32_e32 v20, 0x3377d1cf, v19
	v_fmac_f32_e32 v20, 0x3f317217, v19
	v_cmp_lt_f32_e64 s[2:3], |v19|, s26
	s_nop 1
	v_cndmask_b32_e64 v19, v19, v20, s[2:3]
	v_cndmask_b32_e32 v20, 0, v185, vcc
	v_sub_f32_e32 v59, v19, v20
	v_and_b32_e32 v20, 0xffff0000, v14
	v_max_f32_e32 v20, v20, v20
	v_med3_f32 v20, v20, s8, v184
	v_mul_f32_e32 v20, 0xbfb8aa3b, v20
	v_exp_f32_e32 v20, v20
	v_sub_f32_e32 v19, 1.0, v22
	v_add_f32_e32 v21, 1.0, v20
	v_rcp_f32_e32 v21, v21
	s_nop 0
	v_fmac_f32_e32 v22, v21, v19
	v_cmp_gt_f32_e32 vcc, s75, v22
	s_nop 1
	v_cndmask_b32_e64 v23, 0, 32, vcc
	v_ldexp_f32 v22, v22, v23
	v_log_f32_e32 v22, v22
	s_nop 0
	v_mul_f32_e32 v23, 0x3f317217, v22
	v_fma_f32 v23, v22, s9, -v23
	v_fmac_f32_e32 v23, 0x3377d1cf, v22
	v_fmac_f32_e32 v23, 0x3f317217, v22
	v_cmp_lt_f32_e64 s[2:3], |v22|, s26
	s_nop 1
	v_cndmask_b32_e64 v22, v22, v23, s[2:3]
	v_cndmask_b32_e32 v23, 0, v185, vcc
	v_sub_f32_e32 v61, v22, v23
	v_lshlrev_b32_e32 v23, 16, v14
	v_max_f32_e32 v23, v23, v23
	v_med3_f32 v23, v23, s8, v184
	v_mul_f32_e32 v23, 0xbfb8aa3b, v23
	v_exp_f32_e32 v23, v23
	v_sub_f32_e32 v22, 1.0, v25
	v_add_f32_e32 v24, 1.0, v23
	v_rcp_f32_e32 v24, v24
	s_nop 0
	v_fmac_f32_e32 v25, v24, v22
	v_cmp_gt_f32_e32 vcc, s75, v25
	s_nop 1
	v_cndmask_b32_e64 v26, 0, 32, vcc
	v_ldexp_f32 v25, v25, v26
	v_log_f32_e32 v25, v25
	s_nop 0
	v_mul_f32_e32 v26, 0x3f317217, v25
	v_fma_f32 v26, v25, s9, -v26
	v_fmac_f32_e32 v26, 0x3377d1cf, v25
	v_fmac_f32_e32 v26, 0x3f317217, v25
	v_cmp_lt_f32_e64 s[2:3], |v25|, s26
	s_nop 1
	v_cndmask_b32_e64 v25, v25, v26, s[2:3]
	v_cndmask_b32_e32 v26, 0, v185, vcc
	v_sub_f32_e32 v62, v25, v26
	v_and_b32_e32 v26, 0xffff0000, v13
	v_max_f32_e32 v26, v26, v26
	v_med3_f32 v26, v26, s8, v184
	v_mul_f32_e32 v26, 0xbfb8aa3b, v26
	v_exp_f32_e32 v26, v26
	v_sub_f32_e32 v25, 1.0, v49
	v_add_f32_e32 v27, 1.0, v26
	v_rcp_f32_e32 v27, v27
	s_nop 0
	v_fmac_f32_e32 v49, v27, v25
	v_cmp_gt_f32_e32 vcc, s75, v49
	s_nop 1
	v_cndmask_b32_e64 v51, 0, 32, vcc
	v_ldexp_f32 v49, v49, v51
	v_log_f32_e32 v49, v49
	s_nop 0
	v_mul_f32_e32 v51, 0x3f317217, v49
	v_fma_f32 v51, v49, s9, -v51
	v_fmac_f32_e32 v51, 0x3377d1cf, v49
	v_fmac_f32_e32 v51, 0x3f317217, v49
	v_cmp_lt_f32_e64 s[2:3], |v49|, s26
	s_nop 1
	v_cndmask_b32_e64 v49, v49, v51, s[2:3]
	v_cndmask_b32_e32 v51, 0, v185, vcc
	v_sub_f32_e32 v63, v49, v51
	v_lshlrev_b32_e32 v51, 16, v13
	v_max_f32_e32 v51, v51, v51
	v_med3_f32 v51, v51, s8, v184
	v_mul_f32_e32 v51, 0xbfb8aa3b, v51
	v_exp_f32_e32 v51, v51
	v_sub_f32_e32 v49, 1.0, v54
	v_add_f32_e32 v52, 1.0, v51
	v_rcp_f32_e32 v52, v52
	s_nop 0
	v_fmac_f32_e32 v54, v52, v49
	v_cmp_gt_f32_e32 vcc, s75, v54
	s_nop 1
	v_cndmask_b32_e64 v55, 0, 32, vcc
	v_ldexp_f32 v54, v54, v55
	v_log_f32_e32 v54, v54
	s_nop 0
	v_mul_f32_e32 v55, 0x3f317217, v54
	v_fma_f32 v55, v54, s9, -v55
	v_fmac_f32_e32 v55, 0x3377d1cf, v54
	v_fmac_f32_e32 v55, 0x3f317217, v54
	v_cmp_lt_f32_e64 s[2:3], |v54|, s26
	s_nop 1
	v_cndmask_b32_e64 v54, v54, v55, s[2:3]
	v_cndmask_b32_e32 v55, 0, v185, vcc
	v_sub_f32_e32 v64, v54, v55
	v_and_b32_e32 v54, 0xffff0000, v12
	v_max_f32_e32 v54, v54, v54
	v_med3_f32 v54, v54, s8, v184
	v_mul_f32_e32 v54, 0xbfb8aa3b, v54
	v_exp_f32_e32 v56, v54
	v_sub_f32_e32 v55, 1.0, v53
	v_add_f32_e32 v54, 1.0, v56
	v_rcp_f32_e32 v57, v54
	s_nop 0
	v_fmac_f32_e32 v53, v57, v55
	v_cmp_gt_f32_e32 vcc, s75, v53
	s_nop 1
	v_cndmask_b32_e64 v54, 0, 32, vcc
	v_ldexp_f32 v53, v53, v54
	v_log_f32_e32 v53, v53
	s_nop 0
	v_mul_f32_e32 v54, 0x3f317217, v53
	v_fma_f32 v54, v53, s9, -v54
	v_fmac_f32_e32 v54, 0x3377d1cf, v53
	v_fmac_f32_e32 v54, 0x3f317217, v53
	v_cmp_lt_f32_e64 s[2:3], |v53|, s26
	s_nop 1
	v_cndmask_b32_e64 v53, v53, v54, s[2:3]
	v_cndmask_b32_e32 v54, 0, v185, vcc
	v_sub_f32_e32 v65, v53, v54
	v_lshlrev_b32_e32 v54, 16, v12
	v_max_f32_e32 v54, v54, v54
	v_med3_f32 v54, v54, s8, v184
	v_mul_f32_e32 v54, 0xbfb8aa3b, v54
	v_exp_f32_e32 v54, v54
	v_sub_f32_e32 v53, 1.0, v50
	v_add_f32_e32 v58, 1.0, v54
	v_rcp_f32_e32 v58, v58
	s_nop 0
	v_fmac_f32_e32 v50, v58, v53
	v_mul_f32_e32 v54, v54, v58
	v_cmp_gt_f32_e32 vcc, s75, v50
	v_mul_f32_e32 v58, v54, v53
	s_nop 0
	v_cndmask_b32_e64 v53, 0, 32, vcc
	v_ldexp_f32 v50, v50, v53
	v_log_f32_e32 v50, v50
	s_nop 0
	v_mul_f32_e32 v53, 0x3f317217, v50
	v_fma_f32 v53, v50, s9, -v53
	v_fmac_f32_e32 v53, 0x3377d1cf, v50
	v_fmac_f32_e32 v53, 0x3f317217, v50
	v_cmp_lt_f32_e64 s[2:3], |v50|, s26
	s_nop 1
	v_cndmask_b32_e64 v50, v50, v53, s[2:3]
	v_cndmask_b32_e32 v53, 0, v185, vcc
	v_sub_f32_e32 v66, v50, v53
	v_and_b32_e32 v53, 0xffff0000, v15
	v_max_f32_e32 v53, v53, v53
	v_med3_f32 v53, v53, s8, v184
	v_mul_f32_e32 v53, 0xbfb8aa3b, v53
	v_exp_f32_e32 v53, v53
	v_sub_f32_e32 v50, 1.0, v60
	s_mov_b32 s8, 0x42a00000
	v_add_f32_e32 v54, 1.0, v53
	v_rcp_f32_e32 v54, v54
	s_nop 0
	v_fmac_f32_e32 v60, v54, v50
	v_cmp_gt_f32_e32 vcc, s75, v60
	s_nop 1
	v_cndmask_b32_e64 v67, 0, 32, vcc
	v_ldexp_f32 v60, v60, v67
	v_log_f32_e32 v60, v60
	s_nop 0
	v_mul_f32_e32 v67, 0x3f317217, v60
	v_fma_f32 v67, v60, s9, -v67
	v_fmac_f32_e32 v67, 0x3377d1cf, v60
	v_fmac_f32_e32 v67, 0x3f317217, v60
	v_cmp_lt_f32_e64 s[2:3], |v60|, s26
	s_nop 1
	v_cndmask_b32_e64 v60, v60, v67, s[2:3]
	v_cndmask_b32_e32 v67, 0, v185, vcc
	v_sub_f32_e32 v60, v60, v67
	ds_bpermute_b32 v67, v37, v66
	v_readlane_b32 s2, v249, 32
	s_add_i32 s2, s2, s22
	s_waitcnt lgkmcnt(0)
	v_cndmask_b32_e64 v67, v67, 0, s[40:41]
	v_add_f32_e32 v66, v66, v67
	ds_bpermute_b32 v67, v37, v65
	ds_bpermute_b32 v100, v37, v64
	ds_bpermute_b32 v101, v37, v63
	ds_bpermute_b32 v102, v37, v62
	ds_bpermute_b32 v103, v37, v61
	ds_bpermute_b32 v104, v37, v59
	ds_bpermute_b32 v105, v37, v60
	s_waitcnt lgkmcnt(6)
	v_cndmask_b32_e64 v67, v67, 0, s[40:41]
	v_add_f32_e32 v65, v65, v67
	s_waitcnt lgkmcnt(5)
	v_cndmask_b32_e64 v100, v100, 0, s[40:41]
	v_add_f32_e32 v64, v64, v100
	s_waitcnt lgkmcnt(4)
	v_cndmask_b32_e64 v101, v101, 0, s[40:41]
	v_add_f32_e32 v63, v63, v101
	s_waitcnt lgkmcnt(3)
	v_cndmask_b32_e64 v102, v102, 0, s[40:41]
	v_add_f32_e32 v62, v62, v102
	s_waitcnt lgkmcnt(2)
	v_cndmask_b32_e64 v103, v103, 0, s[40:41]
	v_add_f32_e32 v61, v61, v103
	s_waitcnt lgkmcnt(1)
	v_cndmask_b32_e64 v104, v104, 0, s[40:41]
	v_add_f32_e32 v59, v59, v104
	s_waitcnt lgkmcnt(0)
	v_cndmask_b32_e64 v105, v105, 0, s[40:41]
	v_add_f32_e32 v60, v60, v105
	ds_bpermute_b32 v67, v38, v66
	ds_bpermute_b32 v100, v38, v65
	ds_bpermute_b32 v101, v38, v64
	ds_bpermute_b32 v102, v38, v63
	ds_bpermute_b32 v103, v38, v62
	ds_bpermute_b32 v104, v38, v61
	ds_bpermute_b32 v105, v38, v59
	ds_bpermute_b32 v106, v38, v60
	s_waitcnt lgkmcnt(7)
	v_cndmask_b32_e64 v67, v67, 0, s[42:43]
	v_add_f32_e32 v66, v66, v67
	s_waitcnt lgkmcnt(6)
	v_cndmask_b32_e64 v100, v100, 0, s[42:43]
	v_add_f32_e32 v65, v65, v100
	s_waitcnt lgkmcnt(5)
	v_cndmask_b32_e64 v101, v101, 0, s[42:43]
	v_add_f32_e32 v64, v64, v101
	s_waitcnt lgkmcnt(4)
	v_cndmask_b32_e64 v102, v102, 0, s[42:43]
	v_add_f32_e32 v63, v63, v102
	s_waitcnt lgkmcnt(3)
	v_cndmask_b32_e64 v103, v103, 0, s[42:43]
	v_add_f32_e32 v62, v62, v103
	s_waitcnt lgkmcnt(2)
	v_cndmask_b32_e64 v104, v104, 0, s[42:43]
	v_add_f32_e32 v61, v61, v104
	s_waitcnt lgkmcnt(1)
	v_cndmask_b32_e64 v105, v105, 0, s[42:43]
	v_add_f32_e32 v59, v59, v105
	s_waitcnt lgkmcnt(0)
	v_cndmask_b32_e64 v106, v106, 0, s[42:43]
	v_add_f32_e32 v60, v60, v106
	ds_bpermute_b32 v67, v39, v66
	ds_bpermute_b32 v100, v39, v65
	ds_bpermute_b32 v101, v39, v64
	ds_bpermute_b32 v102, v39, v63
	ds_bpermute_b32 v103, v39, v62
	ds_bpermute_b32 v104, v39, v61
	ds_bpermute_b32 v105, v39, v59
	ds_bpermute_b32 v106, v39, v60
	s_waitcnt lgkmcnt(7)
	v_cndmask_b32_e64 v67, v67, 0, s[44:45]
	v_add_f32_e32 v66, v66, v67
	s_waitcnt lgkmcnt(6)
	v_cndmask_b32_e64 v100, v100, 0, s[44:45]
	v_add_f32_e32 v65, v65, v100
	s_waitcnt lgkmcnt(5)
	v_cndmask_b32_e64 v101, v101, 0, s[44:45]
	v_add_f32_e32 v64, v64, v101
	s_waitcnt lgkmcnt(4)
	v_cndmask_b32_e64 v102, v102, 0, s[44:45]
	v_add_f32_e32 v63, v63, v102
	s_waitcnt lgkmcnt(3)
	v_cndmask_b32_e64 v103, v103, 0, s[44:45]
	v_add_f32_e32 v62, v62, v103
	s_waitcnt lgkmcnt(2)
	v_cndmask_b32_e64 v104, v104, 0, s[44:45]
	v_add_f32_e32 v61, v61, v104
	s_waitcnt lgkmcnt(1)
	v_cndmask_b32_e64 v105, v105, 0, s[44:45]
	v_add_f32_e32 v59, v59, v105
	s_waitcnt lgkmcnt(0)
	v_cndmask_b32_e64 v106, v106, 0, s[44:45]
	v_add_f32_e32 v60, v60, v106
	ds_bpermute_b32 v67, v40, v66
	ds_bpermute_b32 v100, v40, v65
	ds_bpermute_b32 v101, v40, v64
	ds_bpermute_b32 v102, v40, v63
	ds_bpermute_b32 v103, v40, v62
	ds_bpermute_b32 v104, v40, v61
	ds_bpermute_b32 v105, v40, v59
	ds_bpermute_b32 v106, v40, v60
	s_waitcnt lgkmcnt(7)
	v_cndmask_b32_e64 v67, v67, 0, s[46:47]
	v_add_f32_e32 v66, v66, v67
	s_waitcnt lgkmcnt(6)
	v_cndmask_b32_e64 v100, v100, 0, s[46:47]
	v_add_f32_e32 v65, v65, v100
	s_waitcnt lgkmcnt(5)
	v_cndmask_b32_e64 v101, v101, 0, s[46:47]
	v_add_f32_e32 v64, v64, v101
	s_waitcnt lgkmcnt(4)
	v_cndmask_b32_e64 v102, v102, 0, s[46:47]
	v_add_f32_e32 v63, v63, v102
	s_waitcnt lgkmcnt(3)
	v_cndmask_b32_e64 v103, v103, 0, s[46:47]
	v_add_f32_e32 v62, v62, v103
	s_waitcnt lgkmcnt(2)
	v_cndmask_b32_e64 v104, v104, 0, s[46:47]
	v_add_f32_e32 v61, v61, v104
	s_waitcnt lgkmcnt(1)
	v_cndmask_b32_e64 v105, v105, 0, s[46:47]
	v_add_f32_e32 v59, v59, v105
	s_waitcnt lgkmcnt(0)
	v_cndmask_b32_e64 v106, v106, 0, s[46:47]
	v_add_f32_e32 v60, v60, v106
	ds_bpermute_b32 v67, v41, v66
	s_waitcnt lgkmcnt(0)
	v_cndmask_b32_e64 v67, v67, 0, s[48:49]
	v_add_f32_e32 v66, v66, v67
	ds_bpermute_b32 v67, v41, v65
	s_waitcnt lgkmcnt(0)
	v_cndmask_b32_e64 v67, v67, 0, s[48:49]
	v_add_f32_e32 v70, v65, v67
	ds_bpermute_b32 v65, v41, v64
	ds_bpermute_b32 v74, v42, v70
	s_waitcnt lgkmcnt(1)
	v_cndmask_b32_e64 v65, v65, 0, s[48:49]
	v_add_f32_e32 v69, v64, v65
	ds_bpermute_b32 v64, v41, v63
	ds_bpermute_b32 v73, v42, v69
	s_waitcnt lgkmcnt(1)
	v_cndmask_b32_e64 v64, v64, 0, s[48:49]
	v_add_f32_e32 v67, v63, v64
	ds_bpermute_b32 v63, v41, v62
	ds_bpermute_b32 v72, v42, v67
	s_waitcnt lgkmcnt(1)
	v_cndmask_b32_e64 v63, v63, 0, s[48:49]
	v_add_f32_e32 v65, v62, v63
	ds_bpermute_b32 v62, v41, v61
	ds_bpermute_b32 v71, v42, v65
	s_waitcnt lgkmcnt(1)
	v_cndmask_b32_e64 v62, v62, 0, s[48:49]
	v_add_f32_e32 v64, v61, v62
	ds_bpermute_b32 v61, v41, v59
	ds_bpermute_b32 v68, v42, v64
	s_waitcnt lgkmcnt(1)
	v_cndmask_b32_e64 v61, v61, 0, s[48:49]
	v_add_f32_e32 v62, v59, v61
	ds_bpermute_b32 v59, v41, v60
	s_waitcnt lgkmcnt(0)
	v_cndmask_b32_e64 v59, v59, 0, s[48:49]
	v_add_f32_e32 v59, v60, v59
	ds_bpermute_b32 v60, v42, v66
	ds_bpermute_b32 v63, v42, v59
	s_waitcnt lgkmcnt(1)
	v_cndmask_b32_e64 v60, v60, 0, s[50:51]
	v_add_f32_e32 v76, v66, v60
	v_mul_f32_e32 v61, 0x3fb8aa3b, v76
	v_readlane_b32 s3, v76, 63
	v_exp_f32_e32 v75, v61
	v_min_f32_e64 v61, -v76, s8
	v_sub_f32_e32 v76, s3, v76
	v_mul_f32_e32 v61, 0x3fb8aa3b, v61
	v_mul_f32_e32 v76, 0x3fb8aa3b, v76
	v_exp_f32_e32 v61, v61
	v_exp_f32_e32 v76, v76
	ds_bpermute_b32 v66, v42, v62
	v_lshlrev_b32_e32 v60, 16, v8
	v_mul_f32_e32 v61, v58, v61
	v_mul_f32_e32 v58, v58, v76
	v_mul_f32_e32 v60, v75, v60
	v_cvt_pk_bf16_f32 v58, v58, v2
	v_cvt_pk_bf16_f32 v60, v60, v2
	v_cvt_pk_bf16_f32 v61, v61, v2
	ds_write_b16 v43, v58 offset:18432
	s_waitcnt vmcnt(0)
	ds_write_b16 v43, v4 offset:27648
	s_and_saveexec_b64 s[84:85], s[38:39]
	s_cbranch_execz .LBB0_314
	s_ashr_i32 s3, s2, 31
	s_lshl_b64 s[8:9], s[2:3], 2
	s_add_u32 s8, s24, s8
	s_addc_u32 s9, s25, s9
	global_store_dword v2, v75, s[8:9]

.LBB0_332:
	s_lshl_b32 s3, s2, 2
	v_mov_b32_e32 v16, s3
	s_waitcnt lgkmcnt(0)
	global_load_dword v78, v16, s[92:93]
	global_load_dword v79, v16, s[92:93] offset:1024
	global_load_dword v80, v16, s[92:93] offset:4
	global_load_dword v81, v16, s[92:93] offset:1028
	global_load_dword v82, v16, s[92:93] offset:8
	global_load_dword v83, v16, s[92:93] offset:1032
	global_load_dword v84, v16, s[92:93] offset:12
	global_load_dword v85, v16, s[92:93] offset:1036
	global_load_dword v86, v16, s[92:93] offset:16
	global_load_dword v87, v16, s[92:93] offset:1040
	global_load_dword v88, v16, s[92:93] offset:20
	global_load_dword v89, v16, s[92:93] offset:1044
	global_load_dword v90, v16, s[92:93] offset:24
	global_load_dword v91, v16, s[92:93] offset:1048
	global_load_dword v92, v16, s[92:93] offset:28
	global_load_dword v93, v16, s[92:93] offset:1052
	s_waitcnt vmcnt(0)
	v_mov_b32_e32 v17, v78
	v_mov_b32_e32 v16, v79
	v_sub_f32_e32 v16, v17, v16
	v_mul_f32_e32 v16, 0x3fb8aa3b, v16
	v_exp_f32_e32 v16, v16
	s_nop 0
	v_add_f32_e32 v16, 1.0, v16
	v_rcp_f32_e32 v50, v16
	s_and_b64 vcc, exec, s[84:85]
	s_cbranch_vccnz .LBB0_305
.LBB0_333:
	s_lshl_b32 s3, s2, 2
	v_mov_b32_e32 v16, s3
	s_waitcnt lgkmcnt(0)
	v_mov_b32_e32 v17, v80
	s_nop 0
	v_mov_b32_e32 v16, v81
	v_sub_f32_e32 v16, v17, v16
	v_mul_f32_e32 v16, 0x3fb8aa3b, v16
	v_exp_f32_e32 v16, v16
	s_nop 0
	v_add_f32_e32 v16, 1.0, v16
	v_rcp_f32_e32 v53, v16
	v_mov_b32_e32 v49, 0
	s_and_b64 vcc, exec, s[84:85]
	v_mov_b32_e32 v54, 0
	s_cbranch_vccnz .LBB0_306
.LBB0_334:
	s_lshl_b32 s3, s2, 2
	v_mov_b32_e32 v16, s3
	s_waitcnt lgkmcnt(0)
	v_mov_b32_e32 v17, v82
	s_nop 0
	v_mov_b32_e32 v16, v83
	v_sub_f32_e32 v16, v17, v16
	v_mul_f32_e32 v16, 0x3fb8aa3b, v16
	v_exp_f32_e32 v16, v16
	s_nop 0
	v_add_f32_e32 v16, 1.0, v16
	v_rcp_f32_e32 v54, v16
	s_and_b64 vcc, exec, s[84:85]
	s_cbranch_vccnz .LBB0_307
.LBB0_335:
	s_lshl_b32 s3, s2, 2
	v_mov_b32_e32 v16, s3
	s_waitcnt lgkmcnt(0)
	v_mov_b32_e32 v17, v84
	s_nop 0
	v_mov_b32_e32 v16, v85
	v_sub_f32_e32 v16, v17, v16
	v_mul_f32_e32 v16, 0x3fb8aa3b, v16
	v_exp_f32_e32 v16, v16
	s_nop 0
	v_add_f32_e32 v16, 1.0, v16
	v_rcp_f32_e32 v49, v16
	v_mov_b32_e32 v22, 0
	s_and_b64 vcc, exec, s[84:85]
	v_mov_b32_e32 v25, 0
	s_cbranch_vccnz .LBB0_308
.LBB0_336:
	s_lshl_b32 s3, s2, 2
	v_mov_b32_e32 v16, s3
	s_waitcnt lgkmcnt(0)
	v_mov_b32_e32 v17, v86
	s_nop 0
	v_mov_b32_e32 v16, v87
	v_sub_f32_e32 v16, v17, v16
	v_mul_f32_e32 v16, 0x3fb8aa3b, v16
	v_exp_f32_e32 v16, v16
	s_nop 0
	v_add_f32_e32 v16, 1.0, v16
	v_rcp_f32_e32 v25, v16
	s_and_b64 vcc, exec, s[84:85]
	s_cbranch_vccnz .LBB0_309
.LBB0_337:
	s_lshl_b32 s3, s2, 2
	v_mov_b32_e32 v16, s3
	s_waitcnt lgkmcnt(0)
	v_mov_b32_e32 v17, v88
	s_nop 0
	v_mov_b32_e32 v16, v89
	v_sub_f32_e32 v16, v17, v16
	v_mul_f32_e32 v16, 0x3fb8aa3b, v16
	v_exp_f32_e32 v16, v16
	s_nop 0
	v_add_f32_e32 v16, 1.0, v16
	v_rcp_f32_e32 v22, v16
	v_mov_b32_e32 v60, 0
	s_and_b64 vcc, exec, s[84:85]
	v_mov_b32_e32 v19, 0
	s_cbranch_vccnz .LBB0_310
.LBB0_338:
	s_lshl_b32 s3, s2, 2
	v_mov_b32_e32 v16, s3
	s_waitcnt lgkmcnt(0)
	v_mov_b32_e32 v17, v90
	s_nop 0
	v_mov_b32_e32 v16, v91
	v_sub_f32_e32 v16, v17, v16
	v_mul_f32_e32 v16, 0x3fb8aa3b, v16
	v_exp_f32_e32 v16, v16
	s_nop 0
	v_add_f32_e32 v16, 1.0, v16
	v_rcp_f32_e32 v19, v16
	s_and_b64 vcc, exec, s[84:85]
	s_cbranch_vccz .LBB0_311
	s_branch .LBB0_312
